# speedup vs baseline: 1.0170x; 1.0029x over previous
; __device__ __forceinline__ int v_st(int k, int c) { const int kk = (k & ~0xC) | ((k & 4) << 1) | ((k & 8) >> 1); return ((kk >> 3) * 4 + (c >> 5)) * 512 + ((kk & 7) * 32 + (c & 31)) * 2; }
; __device__ __forceinline__ int v_rd_base(int lane) { return ((lane & 3) << 3) | (((lane >> 2) & 3) << 6) | (((lane >> 4) & 1) << 5) | (((lane >> 5) & 1) << 8); }
; __device__ __forceinline__ void diff_block(const Params& p, int s, int h, int qb, char* lds, float lam_full, u16* Odst) {
;     ...
;   const int sr = tid >> 4, sc = (tid & 15) * 8, vst0 = v_st(sr, sc), vst1 = v_st(32 + sr, sc);
;   const int vb0 = (int)(uintptr_t)V_lds + v_rd_base(lane);
;   const int cbyte0 = map * 128;
;   const u16* Kh = Kp + (long)base * DM + h * 128;
;   const u16* Vh = Vp + (long)base * DM + h * 128;
;   struct { bf16x8 vs0, vs1, ks0, ks1; } sr_[2];
;   const unsigned soff0 = (unsigned)(sr * DM + sc) * 2u;
; __device__ __forceinline__ void phase_diff(const Params& p, char* lds, u16* Odst) {
;   float d01 = 0.f, d23 = 0.f;
;   for (int i = 0; i < 64; ++i) { d01 += p.lambda_b[i] * p.lambda_b[64 + i]; d23 += p.lambda_b[128 + i] * p.lambda_b[192 + i]; }
;   const float lam_full = __expf(d01) - __expf(d23) + LAMBDA_INIT;
.LBB0_227:
	s_add_u32 s2, s12, s0
	s_addc_u32 s3, s13, s1
	global_load_dwordx4 v[2:5], v97, s[2:3] offset:48
	global_load_dwordx4 v[6:9], v97, s[2:3] offset:32
	global_load_dwordx4 v[10:13], v97, s[2:3] offset:16
	global_load_dwordx4 v[14:17], v97, s[2:3]
	global_load_dwordx4 v[18:21], v97, s[2:3] offset:304
	global_load_dwordx4 v[22:25], v97, s[2:3] offset:288
	global_load_dwordx4 v[26:29], v97, s[2:3] offset:272
	global_load_dwordx4 v[30:33], v97, s[2:3] offset:256
	global_load_dwordx4 v[34:37], v97, s[2:3] offset:560
	global_load_dwordx4 v[38:41], v97, s[2:3] offset:544
	global_load_dwordx4 v[42:45], v97, s[2:3] offset:528
	global_load_dwordx4 v[46:49], v97, s[2:3] offset:512
	global_load_dwordx4 v[50:53], v97, s[2:3] offset:816
	global_load_dwordx4 v[54:57], v97, s[2:3] offset:800
	global_load_dwordx4 v[58:61], v97, s[2:3] offset:784
	global_load_dwordx4 v[62:65], v97, s[2:3] offset:768
	s_add_u32 s0, s0, 64
	s_addc_u32 s1, s1, 0
	s_cmpk_eq_i32 s0, 0x100
	s_waitcnt vmcnt(0)
	v_mov_b32_e32 v66, v14
	v_mov_b32_e32 v14, v16
	v_mov_b32_e32 v16, v26
	v_mov_b32_e32 v68, v30
	v_mov_b32_e32 v30, v32
	v_mov_b32_e32 v67, v46
	v_mov_b32_e32 v46, v15
	v_mov_b32_e32 v15, v48
	v_mov_b32_e32 v48, v17
	v_mov_b32_e32 v69, v62
	v_pk_fma_f32 v[0:1], v[66:67], v[68:69], v[0:1]
	v_mov_b32_e32 v62, v31
	v_pk_fma_f32 v[0:1], v[46:47], v[62:63], v[0:1]
	v_mov_b32_e32 v31, v64
	v_pk_fma_f32 v[0:1], v[14:15], v[30:31], v[0:1]
	v_mov_b32_e32 v64, v33
	v_pk_fma_f32 v[0:1], v[48:49], v[64:65], v[0:1]
	v_mov_b32_e32 v14, v10
	v_mov_b32_e32 v15, v42
	v_mov_b32_e32 v17, v58
	v_pk_fma_f32 v[0:1], v[14:15], v[16:17], v[0:1]
	v_mov_b32_e32 v42, v11
	v_mov_b32_e32 v58, v27
	v_pk_fma_f32 v[0:1], v[42:43], v[58:59], v[0:1]
	v_mov_b32_e32 v10, v12
	v_mov_b32_e32 v11, v44
	v_mov_b32_e32 v14, v28
	v_mov_b32_e32 v15, v60
	v_pk_fma_f32 v[0:1], v[10:11], v[14:15], v[0:1]
	v_mov_b32_e32 v44, v13
	v_mov_b32_e32 v60, v29
	v_pk_fma_f32 v[0:1], v[44:45], v[60:61], v[0:1]
	v_mov_b32_e32 v10, v6
	v_mov_b32_e32 v11, v38
	v_mov_b32_e32 v12, v22
	v_mov_b32_e32 v13, v54
	v_pk_fma_f32 v[0:1], v[10:11], v[12:13], v[0:1]
	v_mov_b32_e32 v38, v7
	v_mov_b32_e32 v54, v23
	v_pk_fma_f32 v[0:1], v[38:39], v[54:55], v[0:1]
	v_mov_b32_e32 v6, v8
	v_mov_b32_e32 v7, v40
	v_mov_b32_e32 v10, v24
	v_mov_b32_e32 v11, v56
	v_pk_fma_f32 v[0:1], v[6:7], v[10:11], v[0:1]
	v_mov_b32_e32 v40, v9
	v_mov_b32_e32 v56, v25
	v_pk_fma_f32 v[0:1], v[40:41], v[56:57], v[0:1]
	v_mov_b32_e32 v6, v2
	v_mov_b32_e32 v7, v34
	v_mov_b32_e32 v8, v18
	v_mov_b32_e32 v9, v50
	v_pk_fma_f32 v[0:1], v[6:7], v[8:9], v[0:1]
	v_mov_b32_e32 v34, v3
	v_mov_b32_e32 v50, v19
	v_pk_fma_f32 v[0:1], v[34:35], v[50:51], v[0:1]
	v_mov_b32_e32 v2, v4
	v_mov_b32_e32 v3, v36
	v_mov_b32_e32 v6, v20
	v_mov_b32_e32 v7, v52
	v_pk_fma_f32 v[0:1], v[2:3], v[6:7], v[0:1]
	v_mov_b32_e32 v36, v5
	v_mov_b32_e32 v52, v21
	v_pk_fma_f32 v[0:1], v[36:37], v[52:53], v[0:1]
	s_cbranch_scc0 .LBB0_227
	v_lshrrev_b32_e32 v247, 6, v184
	v_bfe_u32 v246, v184, 4, 3
	v_readfirstlane_b32 s100, v247
	v_lshlrev_b32_e32 v246, 4, v246
	v_bfe_u32 v247, v184, 2, 3
	v_lshrrev_b32_e32 v248, 7, v184
	v_lshl_or_b32 v247, v248, 3, v247
	s_lshl_b32 s100, s100, 10
	v_and_b32_e32 v248, 0x33, v247
	v_and_b32_e32 v249, 4, v247
	v_lshl_or_b32 v248, v249, 1, v248
	v_and_b32_e32 v249, 8, v247
	v_lshrrev_b32_e32 v249, 1, v249
	v_or_b32_e32 v248, v248, v249
	v_bfe_u32 v249, v184, 5, 2
	v_and_b32_e32 v250, 3, v184
	v_lshlrev_b32_e32 v250, 4, v250
	v_lshl_or_b32 v249, v249, 6, v250
	v_lshl_or_b32 v245, v248, 11, v249
	v_lshrrev_b32_e32 v248, 4, v184
	v_and_b32_e32 v249, 15, v184
	v_lshlrev_b32_e32 v249, 4, v249
	v_lshl_or_b32 v248, v248, 11, v249
	v_sub_u32_e32 v245, v245, v248
	v_mul_f32_e32 v0, 0x3fb8aa3b, v0
	v_mul_f32_e32 v1, 0x3fb8aa3b, v1
	v_exp_f32_e32 v0, v0
	v_exp_f32_e32 v1, v1
	v_readlane_b32 s2, v254, 12
	v_readlane_b32 s0, v253, 1
	v_readlane_b32 s3, v254, 13
	v_sub_f32_e32 v0, v0, v1
	v_add_f32_e32 v162, 0x3eb60549, v0
	s_andn2_b64 vcc, exec, s[2:3]
	s_ashr_i32 s14, s0, 3
	s_cbranch_vccnz .LBB0_277
	v_mov_b32_e32 v163, v162
	v_readlane_b32 s15, v254, 18
	s_branch .LBB0_231

; #define SBAR() __builtin_amdgcn_sched_barrier(0)
; __device__ __forceinline__ void diff_block(const Params& p, int s, int h, int qb, char* lds, float lam_full, u16* Odst) {
;     ...
;   for (int j = 1; j + 1 < NT; j += 2) {
;     SBAR(); da_qkt(pB0, pB1, K_lds + cK, qr, r32, hi, cbyte0);
;     da_finish2(pA0, pA1, m_reg, l_reg, alA, pa0, pa1, pa2, pa3); SBAR();
.LBB0_239:
	s_mov_b32 s4, s0
	v_add_u32_e32 v68, s12, v223
	ds_read_b128 v[64:67], v68 offset:49152
	ds_read_b128 v[68:71], v68 offset:57344
	v_add_u32_e32 v134, s12, v220
	ds_read_b128 v[130:133], v134 offset:49152
	ds_read_b128 v[134:137], v134 offset:57344
	v_exp_f32_e32 v144, v164
	s_add_u32 s101, s4, s100
	v_add_u32_e32 v247, 0xfffb0000, v227
	s_mov_b32 m0, s101
	v_add_u32_e32 v248, v245, v247
	global_load_lds_dwordx4 v248, s[8:9]
	s_add_u32 m0, s101, 0x2000
	v_add_u32_e32 v248, 0x10000, v248
	global_load_lds_dwordx4 v248, s[8:9]
	s_add_u32 m0, s101, 0xc000
	v_xor_b32_e32 v248, v246, v247
	global_load_lds_dwordx4 v248, s[2:3]
	s_add_u32 m0, s101, 0xe000
	v_add_u32_e32 v248, 0x10000, v248
	global_load_lds_dwordx4 v248, s[2:3]
	s_waitcnt lgkmcnt(3)
	v_mfma_f32_32x32x16_bf16 v[80:95], v[64:67], v[110:113], 0
	v_add_f32_e32 v164, 0, v146
	v_add_f32_e32 v164, v147, v164
	v_add_f32_e32 v164, v148, v164
	v_add_f32_e32 v164, v149, v164
	v_add_f32_e32 v164, v150, v164
	v_add_f32_e32 v164, v151, v164
	v_add_f32_e32 v164, v160, v164
	s_waitcnt lgkmcnt(2)
	v_mfma_f32_32x32x16_bf16 v[64:79], v[68:71], v[110:113], 0
	v_add_f32_e32 v164, v161, v164
	v_add_f32_e32 v164, v158, v164
	v_add_f32_e32 v164, v159, v164
	v_add_f32_e32 v164, v156, v164
	v_add_f32_e32 v164, v157, v164
	v_add_f32_e32 v164, v152, v164
	v_add_f32_e32 v164, v153, v164
	s_waitcnt lgkmcnt(1)
	v_mfma_f32_32x32x16_bf16 v[80:95], v[130:133], v[106:109], v[80:95]
	v_add_f32_e32 v164, v154, v164
	v_add_f32_e32 v164, v155, v164
	v_exp_f32_e32 v138, v174
	v_exp_f32_e32 v139, v175
	v_exp_f32_e32 v140, v168
	v_exp_f32_e32 v141, v169
	v_exp_f32_e32 v142, v166
	s_waitcnt lgkmcnt(0)
	v_mfma_f32_32x32x16_bf16 v[64:79], v[134:137], v[106:109], v[64:79]
	v_add_u32_e32 v134, s12, v219
	ds_read_b128 v[130:133], v134 offset:49152
	ds_read_b128 v[134:137], v134 offset:57344
	v_exp_f32_e32 v143, v167
	v_exp_f32_e32 v145, v165
	s_waitcnt lgkmcnt(1)
	v_mfma_f32_32x32x16_bf16 v[80:95], v[130:133], v[102:105], v[80:95]
	s_waitcnt lgkmcnt(0)
	v_mfma_f32_32x32x16_bf16 v[64:79], v[134:137], v[102:105], v[64:79]
	v_add_u32_e32 v134, s12, v218
	ds_read_b128 v[130:133], v134 offset:49152
	ds_read_b128 v[134:137], v134 offset:57344
	s_waitcnt lgkmcnt(1)
	v_mfma_f32_32x32x16_bf16 v[80:95], v[130:133], v[98:101], v[80:95]
	v_exp_f32_e32 v130, v176
	v_exp_f32_e32 v131, v177
	v_exp_f32_e32 v132, v172
	v_exp_f32_e32 v133, v173
	v_add_f32_e32 v164, v130, v164
	v_add_f32_e32 v164, v131, v164
	v_add_f32_e32 v164, v132, v164
	s_waitcnt lgkmcnt(0)
	v_mfma_f32_32x32x16_bf16 v[64:79], v[134:137], v[98:101], v[64:79]
	v_exp_f32_e32 v134, v178
	v_exp_f32_e32 v135, v179
	v_add_f32_e32 v164, v133, v164
	v_exp_f32_e32 v136, v170
	v_add_f32_e32 v164, v134, v164
	v_exp_f32_e32 v137, v171
	v_add_f32_e32 v164, v135, v164
	v_add_f32_e32 v164, v138, v164
	v_add_f32_e32 v164, v139, v164
	v_add_f32_e32 v164, v136, v164
	v_add_f32_e32 v164, v137, v164
	v_add_f32_e32 v164, v140, v164
	v_add_f32_e32 v164, v141, v164
	v_add_f32_e32 v164, v142, v164
	v_add_f32_e32 v164, v143, v164
	v_add_f32_e32 v164, v144, v164
	v_add_f32_e32 v165, v145, v164
	v_cmp_gt_f32_e32 vcc, s34, v165
	s_cmp_eq_u64 vcc, exec
	v_mov_b32_e32 v164, 1.0
	s_cbranch_scc0 .LBB0_254

; #define SBAR() __builtin_amdgcn_sched_barrier(0)
; #define SLOAD(i, k0) do { const unsigned o0_ = soff0 + (unsigned)(k0) * (DM * 2u), o1_ = o0_ + 32u * DM * 2u;                 \
;     sr_[i].vs0 = *(const bf16x8*)((const char*)Vh + (size_t)o0_); sr_[i].vs1 = *(const bf16x8*)((const char*)Vh + (size_t)o1_); \
;     sr_[i].ks0 = *(const bf16x8*)((const char*)Kh + (size_t)o0_); sr_[i].ks1 = *(const bf16x8*)((const char*)Kh + (size_t)o1_); } while (0)
; #define SWRITE(boff, i) do { *(bf16x8*)(V_lds + (boff) + vst0) = sr_[i].vs0;          \
;     *(bf16x8*)(V_lds + (boff) + vst1) = sr_[i].vs1; int kc = sc * 2;               \
;     *(bf16x8*)(K_lds + (boff) + KSWZ(sr, kc)) = sr_[i].ks0;                       \
;     *(bf16x8*)(K_lds + (boff) + KSWZ(32 + sr, kc)) = sr_[i].ks1; } while (0)
; #define SWAIT() asm volatile("s_waitcnt vmcnt(4)" ::: "memory")
; template <int D0> __device__ __forceinline__ void pv_one(f32x16& od, int vb, bf16x8 pa0, bf16x8 pa1, bf16x8 pa2, bf16x8 pa3) {
;   const s16x4 l0 = tr_read<v_rd_off(D0, 0, 0)>(vb), h0 = tr_read<v_rd_off(D0, 0, 1)>(vb), l1 = tr_read<v_rd_off(D0, 1, 0)>(vb), h1 = tr_read<v_rd_off(D0, 1, 1)>(vb);
;   const s16x4 l2 = tr_read<v_rd_off(D0, 2, 0)>(vb), h2 = tr_read<v_rd_off(D0, 2, 1)>(vb), l3 = tr_read<v_rd_off(D0, 3, 0)>(vb), h3 = tr_read<v_rd_off(D0, 3, 1)>(vb);
;   asm volatile("s_waitcnt lgkmcnt(0)" ::: "memory"); SBAR();
;     ...
;   od = __builtin_amdgcn_mfma_f32_32x32x16_bf16(pa0, PK(l0, h0), od, 0, 0, 0);
;   od = __builtin_amdgcn_mfma_f32_32x32x16_bf16(pa1, PK(l1, h1), od, 0, 0, 0);
;   od = __builtin_amdgcn_mfma_f32_32x32x16_bf16(pa2, PK(l2, h2), od, 0, 0, 0);
;   od = __builtin_amdgcn_mfma_f32_32x32x16_bf16(pa3, PK(l3, h3), od, 0, 0, 0);
; __device__ __forceinline__ void diff_block(const Params& p, int s, int h, int qb, char* lds, float lam_full, u16* Odst) {
;     ...
;     SLOAD(SO, (j + 2) * 64); SBAR();
;     da_pv(o, vb0 + pV, pa0, pa1, pa2, pa3); da_partial2(pB0, pB1, m_reg);
;     SWAIT(); SWRITE(nW, SE);
;     __syncthreads();
.LBB0_244:
	v_add_u32_e32 v224, s10, v214
	ds_read_b64_tr_b16 v[166:167], v224 offset:0
	ds_read_b64_tr_b16 v[168:169], v224 offset:0x800
	ds_read_b64_tr_b16 v[170:171], v224 offset:0x1000
	ds_read_b64_tr_b16 v[172:173], v224 offset:0x1800
	ds_read_b64_tr_b16 v[174:175], v224 offset:0x2000
	ds_read_b64_tr_b16 v[176:177], v224 offset:0x2800
	ds_read_b64_tr_b16 v[178:179], v224 offset:0x3000
	ds_read_b64_tr_b16 v[180:181], v224 offset:0x3800
	s_waitcnt lgkmcnt(0)
	s_nop 0
	v_mfma_f32_32x32x16_bf16 v[0:15], v[146:149], v[166:169], v[0:15]
	ds_read_b64_tr_b16 v[166:167], v224 offset:0x200
	ds_read_b64_tr_b16 v[168:169], v224 offset:0xa00
	v_mfma_f32_32x32x16_bf16 v[0:15], v[150:153], v[170:173], v[0:15]
	ds_read_b64_tr_b16 v[170:171], v224 offset:0x1200
	ds_read_b64_tr_b16 v[172:173], v224 offset:0x1a00
	v_mfma_f32_32x32x16_bf16 v[0:15], v[154:157], v[174:177], v[0:15]
	ds_read_b64_tr_b16 v[174:175], v224 offset:0x2200
	ds_read_b64_tr_b16 v[176:177], v224 offset:0x2a00
	v_mfma_f32_32x32x16_bf16 v[0:15], v[158:161], v[178:181], v[0:15]
	ds_read_b64_tr_b16 v[178:179], v224 offset:0x3200
	ds_read_b64_tr_b16 v[180:181], v224 offset:0x3a00
	s_waitcnt lgkmcnt(0)
	v_mfma_f32_32x32x16_bf16 v[16:31], v[146:149], v[166:169], v[16:31]
	ds_read_b64_tr_b16 v[166:167], v224 offset:0x400
	ds_read_b64_tr_b16 v[168:169], v224 offset:0xc00
	v_mul_f32_e32 v196, 0xbe38aa3b, v213
	v_fmamk_f32 v80, v80, 0x3e38aa3b, v196
	v_fmamk_f32 v81, v81, 0x3e38aa3b, v196
	v_fmamk_f32 v82, v82, 0x3e38aa3b, v196
	v_mfma_f32_32x32x16_bf16 v[16:31], v[150:153], v[170:173], v[16:31]
	ds_read_b64_tr_b16 v[170:171], v224 offset:0x1400
	ds_read_b64_tr_b16 v[172:173], v224 offset:0x1c00
	v_fmamk_f32 v83, v83, 0x3e38aa3b, v196
	v_fmamk_f32 v84, v84, 0x3e38aa3b, v196
	v_fmamk_f32 v85, v85, 0x3e38aa3b, v196
	v_fmamk_f32 v86, v86, 0x3e38aa3b, v196
	v_mfma_f32_32x32x16_bf16 v[16:31], v[154:157], v[174:177], v[16:31]
	ds_read_b64_tr_b16 v[174:175], v224 offset:0x2400
	ds_read_b64_tr_b16 v[176:177], v224 offset:0x2c00
	v_fmamk_f32 v87, v87, 0x3e38aa3b, v196
	v_fmamk_f32 v88, v88, 0x3e38aa3b, v196
	v_fmamk_f32 v89, v89, 0x3e38aa3b, v196
	v_fmamk_f32 v90, v90, 0x3e38aa3b, v196
	v_mfma_f32_32x32x16_bf16 v[16:31], v[158:161], v[178:181], v[16:31]
	ds_read_b64_tr_b16 v[178:179], v224 offset:0x3400
	ds_read_b64_tr_b16 v[180:181], v224 offset:0x3c00
	v_fmamk_f32 v91, v91, 0x3e38aa3b, v196
	v_fmamk_f32 v92, v92, 0x3e38aa3b, v196
	v_fmamk_f32 v93, v93, 0x3e38aa3b, v196
	v_fmamk_f32 v94, v94, 0x3e38aa3b, v196
	s_waitcnt lgkmcnt(0)
	v_mfma_f32_32x32x16_bf16 v[32:47], v[146:149], v[166:169], v[32:47]
	ds_read_b64_tr_b16 v[166:167], v224 offset:0x600
	ds_read_b64_tr_b16 v[168:169], v224 offset:0xe00
	v_fmamk_f32 v95, v95, 0x3e38aa3b, v196
	v_fmamk_f32 v197, v70, 0x3e38aa3b, v196
	v_fmamk_f32 v198, v71, 0x3e38aa3b, v196
	v_fmamk_f32 v199, v72, 0x3e38aa3b, v196
	v_mfma_f32_32x32x16_bf16 v[32:47], v[150:153], v[170:173], v[32:47]
	ds_read_b64_tr_b16 v[170:171], v224 offset:0x1600
	ds_read_b64_tr_b16 v[172:173], v224 offset:0x1e00
	v_fmamk_f32 v200, v73, 0x3e38aa3b, v196
	v_fmamk_f32 v201, v74, 0x3e38aa3b, v196
	v_fmamk_f32 v202, v75, 0x3e38aa3b, v196
	v_fmamk_f32 v203, v76, 0x3e38aa3b, v196
	v_mfma_f32_32x32x16_bf16 v[32:47], v[154:157], v[174:177], v[32:47]
	ds_read_b64_tr_b16 v[174:175], v224 offset:0x2600
	ds_read_b64_tr_b16 v[176:177], v224 offset:0x2e00
	v_fmamk_f32 v204, v77, 0x3e38aa3b, v196
	v_fmamk_f32 v205, v78, 0x3e38aa3b, v196
	v_mfma_f32_32x32x16_bf16 v[32:47], v[158:161], v[178:181], v[32:47]
	ds_read_b64_tr_b16 v[178:179], v224 offset:0x3600
	ds_read_b64_tr_b16 v[180:181], v224 offset:0x3e00
	s_waitcnt lgkmcnt(0)
	v_mfma_f32_32x32x16_bf16 v[48:63], v[146:149], v[166:169], v[48:63]
	v_exp_f32_e32 v146, v80
	v_exp_f32_e32 v147, v81
	v_exp_f32_e32 v148, v84
	v_exp_f32_e32 v149, v85
	v_mfma_f32_32x32x16_bf16 v[48:63], v[150:153], v[170:173], v[48:63]
	v_exp_f32_e32 v150, v88
	v_exp_f32_e32 v151, v89
	v_exp_f32_e32 v152, v92
	v_exp_f32_e32 v153, v93
	v_mfma_f32_32x32x16_bf16 v[48:63], v[154:157], v[174:177], v[48:63]
	v_exp_f32_e32 v154, v94
	v_exp_f32_e32 v155, v95
	v_exp_f32_e32 v156, v90
	v_exp_f32_e32 v157, v91
	v_fmamk_f32 v174, v64, 0x3e38aa3b, v196
	v_fmamk_f32 v175, v65, 0x3e38aa3b, v196
	v_mfma_f32_32x32x16_bf16 v[48:63], v[158:161], v[178:181], v[48:63]
	v_exp_f32_e32 v158, v86
	v_exp_f32_e32 v159, v87
	v_exp_f32_e32 v160, v82
	v_exp_f32_e32 v161, v83
	v_fmamk_f32 v178, v66, 0x3e38aa3b, v196
	v_fmamk_f32 v179, v67, 0x3e38aa3b, v196
	v_fmamk_f32 v180, v68, 0x3e38aa3b, v196
	v_fmamk_f32 v181, v69, 0x3e38aa3b, v196
	v_fmac_f32_e32 v196, 0x3e38aa3b, v79
	s_waitcnt vmcnt(0) lgkmcnt(0)
	s_barrier
; #define SBAR() __builtin_amdgcn_sched_barrier(0)
; #define SLOAD(i, k0) do { const unsigned o0_ = soff0 + (unsigned)(k0) * (DM * 2u), o1_ = o0_ + 32u * DM * 2u;                 \
;     sr_[i].vs0 = *(const bf16x8*)((const char*)Vh + (size_t)o0_); sr_[i].vs1 = *(const bf16x8*)((const char*)Vh + (size_t)o1_); \
;     sr_[i].ks0 = *(const bf16x8*)((const char*)Kh + (size_t)o0_); sr_[i].ks1 = *(const bf16x8*)((const char*)Kh + (size_t)o1_); } while (0)
; #define RESC(a) do { if (__any((a) < 1.f)) { if (hi == 0) al_l[r32] = (a); asm volatile("s_waitcnt lgkmcnt(0)" ::: "memory"); \
;     _Pragma("unroll") for (int d = 0; d < 4; ++d) _Pragma("unroll") for (int r = 0; r < 16; ++r) o[d][r] *= al_l[crow(r, hi)]; } } while (0)
; __device__ __forceinline__ void diff_block(const Params& p, int s, int h, int qb, char* lds, float lam_full, u16* Odst) {
;     ...
;     SBAR(); da_qkt(pA0, pA1, K_lds + cK, qr, r32, hi, cbyte0);
;     da_finish2(pB0, pB1, m_reg, l_reg, alB, pa0, pa1, pa2, pa3); SBAR();
;     RESC(alB);
;     if (j + 3 < NT) SLOAD(SE, (j + 3) * 64); SBAR();
	v_add_u32_e32 v68, s4, v223
	ds_read_b128 v[64:67], v68 offset:49152
	ds_read_b128 v[68:71], v68 offset:57344
	v_add_u32_e32 v170, s4, v220
	ds_read_b128 v[166:169], v170 offset:49152
	ds_read_b128 v[170:173], v170 offset:57344
	v_exp_f32_e32 v176, v174
	s_add_u32 s101, s10, s100
	v_add_u32_e32 v247, 0xfffd0000, v227
	s_mov_b32 m0, s101
	v_add_u32_e32 v248, v245, v247
	global_load_lds_dwordx4 v248, s[8:9]
	s_add_u32 m0, s101, 0x2000
	v_add_u32_e32 v248, 0x10000, v248
	global_load_lds_dwordx4 v248, s[8:9]
	s_add_u32 m0, s101, 0xc000
	v_xor_b32_e32 v248, v246, v247
	global_load_lds_dwordx4 v248, s[2:3]
	s_add_u32 m0, s101, 0xe000
	v_add_u32_e32 v248, 0x10000, v248
	global_load_lds_dwordx4 v248, s[2:3]
	s_waitcnt lgkmcnt(3)
	v_mfma_f32_32x32x16_bf16 v[80:95], v[64:67], v[110:113], 0
	v_exp_f32_e32 v177, v175
	v_exp_f32_e32 v182, v178
	v_exp_f32_e32 v183, v179
	v_exp_f32_e32 v180, v180
	v_exp_f32_e32 v181, v181
	v_exp_f32_e32 v178, v197
	v_exp_f32_e32 v179, v198
	s_waitcnt lgkmcnt(2)
	v_mfma_f32_32x32x16_bf16 v[64:79], v[68:71], v[110:113], 0
	v_exp_f32_e32 v174, v199
	v_exp_f32_e32 v175, v200
	s_waitcnt lgkmcnt(1)
	v_mfma_f32_32x32x16_bf16 v[80:95], v[166:169], v[106:109], v[80:95]
	s_waitcnt lgkmcnt(0)
	v_mfma_f32_32x32x16_bf16 v[64:79], v[170:173], v[106:109], v[64:79]
	v_add_u32_e32 v170, s4, v219
	ds_read_b128 v[166:169], v170 offset:49152
	ds_read_b128 v[170:173], v170 offset:57344
	s_waitcnt lgkmcnt(1)
	v_mfma_f32_32x32x16_bf16 v[80:95], v[166:169], v[102:105], v[80:95]
	s_waitcnt lgkmcnt(0)
	v_mfma_f32_32x32x16_bf16 v[64:79], v[170:173], v[102:105], v[64:79]
	v_add_u32_e32 v170, s4, v218
	ds_read_b128 v[166:169], v170 offset:49152
	ds_read_b128 v[170:173], v170 offset:57344
	s_waitcnt lgkmcnt(1)
	v_mfma_f32_32x32x16_bf16 v[80:95], v[166:169], v[98:101], v[80:95]
	v_add_f32_e32 v166, 0, v146
	v_add_f32_e32 v166, v147, v166
	v_add_f32_e32 v166, v160, v166
	v_add_f32_e32 v166, v161, v166
	v_add_f32_e32 v166, v148, v166
	v_add_f32_e32 v166, v149, v166
	v_add_f32_e32 v166, v158, v166
	v_add_f32_e32 v166, v159, v166
	v_add_f32_e32 v166, v150, v166
	v_add_f32_e32 v166, v151, v166
	v_add_f32_e32 v166, v156, v166
	v_add_f32_e32 v166, v157, v166
	v_add_f32_e32 v166, v152, v166
	v_add_f32_e32 v166, v153, v166
	v_add_f32_e32 v166, v154, v166
	v_add_f32_e32 v166, v155, v166
	v_add_f32_e32 v166, v176, v166
	v_add_f32_e32 v166, v177, v166
	v_add_f32_e32 v166, v182, v166
	v_add_f32_e32 v166, v183, v166
	v_add_f32_e32 v166, v180, v166
	v_add_f32_e32 v166, v181, v166
	s_waitcnt lgkmcnt(0)
	v_mfma_f32_32x32x16_bf16 v[64:79], v[170:173], v[98:101], v[64:79]
	v_exp_f32_e32 v172, v201
	v_add_f32_e32 v166, v178, v166
	v_exp_f32_e32 v173, v202
	v_add_f32_e32 v166, v179, v166
	v_exp_f32_e32 v170, v203
	v_add_f32_e32 v166, v174, v166
	v_exp_f32_e32 v171, v204
	v_add_f32_e32 v166, v175, v166
	v_exp_f32_e32 v168, v205
	v_add_f32_e32 v166, v172, v166
	v_exp_f32_e32 v169, v196
	v_add_f32_e32 v166, v173, v166
	v_add_f32_e32 v166, v170, v166
	v_add_f32_e32 v166, v171, v166
	v_add_f32_e32 v166, v168, v166
	v_add_f32_e32 v225, v169, v166
	v_cmp_gt_f32_e32 vcc, s34, v225
	s_cmp_eq_u64 vcc, exec
	s_cbranch_scc0 .LBB0_255
	v_mov_b32_e32 v166, 1.0

; #define SBAR() __builtin_amdgcn_sched_barrier(0)
; #define SLOAD(i, k0) do { const unsigned o0_ = soff0 + (unsigned)(k0) * (DM * 2u), o1_ = o0_ + 32u * DM * 2u;                 \
;     sr_[i].vs0 = *(const bf16x8*)((const char*)Vh + (size_t)o0_); sr_[i].vs1 = *(const bf16x8*)((const char*)Vh + (size_t)o1_); \
;     sr_[i].ks0 = *(const bf16x8*)((const char*)Kh + (size_t)o0_); sr_[i].ks1 = *(const bf16x8*)((const char*)Kh + (size_t)o1_); } while (0)
; #define SWRITE(boff, i) do { *(bf16x8*)(V_lds + (boff) + vst0) = sr_[i].vs0;          \
;     *(bf16x8*)(V_lds + (boff) + vst1) = sr_[i].vs1; int kc = sc * 2;               \
;     *(bf16x8*)(K_lds + (boff) + KSWZ(sr, kc)) = sr_[i].ks0;                       \
;     *(bf16x8*)(K_lds + (boff) + KSWZ(32 + sr, kc)) = sr_[i].ks1; } while (0)
; #define SWAIT() asm volatile("s_waitcnt vmcnt(4)" ::: "memory")
; #define ROT() do { const int t_ = pV; pV = cK; cK = nW; nW = t_; } while (0)
; template <int D0> __device__ __forceinline__ void pv_one(f32x16& od, int vb, bf16x8 pa0, bf16x8 pa1, bf16x8 pa2, bf16x8 pa3) {
;   const s16x4 l0 = tr_read<v_rd_off(D0, 0, 0)>(vb), h0 = tr_read<v_rd_off(D0, 0, 1)>(vb), l1 = tr_read<v_rd_off(D0, 1, 0)>(vb), h1 = tr_read<v_rd_off(D0, 1, 1)>(vb);
;   const s16x4 l2 = tr_read<v_rd_off(D0, 2, 0)>(vb), h2 = tr_read<v_rd_off(D0, 2, 1)>(vb), l3 = tr_read<v_rd_off(D0, 3, 0)>(vb), h3 = tr_read<v_rd_off(D0, 3, 1)>(vb);
;   asm volatile("s_waitcnt lgkmcnt(0)" ::: "memory"); SBAR();
;     ...
;   od = __builtin_amdgcn_mfma_f32_32x32x16_bf16(pa0, PK(l0, h0), od, 0, 0, 0);
;   od = __builtin_amdgcn_mfma_f32_32x32x16_bf16(pa1, PK(l1, h1), od, 0, 0, 0);
;   od = __builtin_amdgcn_mfma_f32_32x32x16_bf16(pa2, PK(l2, h2), od, 0, 0, 0);
;   od = __builtin_amdgcn_mfma_f32_32x32x16_bf16(pa3, PK(l3, h3), od, 0, 0, 0);
; __device__ __forceinline__ void diff_block(const Params& p, int s, int h, int qb, char* lds, float lam_full, u16* Odst) {
;     ...
;     if (j + 3 < NT) SLOAD(SE, (j + 3) * 64); SBAR();
;     da_pv(o, vb0 + pV, pa0, pa1, pa2, pa3); da_partial2(pA0, pA1, m_reg);
;     SWAIT(); SWRITE(nW, SO);
;     __syncthreads();
;     ROT();
.LBB0_250:
.LBB0_252:
	v_fmac_f32_e32 v165, v226, v164
	v_fmac_f32_e32 v225, v165, v166
	v_add_u32_e32 v180, s12, v214
	ds_read_b64_tr_b16 v[164:165], v180 offset:0
	ds_read_b64_tr_b16 v[166:167], v180 offset:0x800
	ds_read_b64_tr_b16 v[168:169], v180 offset:0x1000
	ds_read_b64_tr_b16 v[170:171], v180 offset:0x1800
	ds_read_b64_tr_b16 v[172:173], v180 offset:0x2000
	ds_read_b64_tr_b16 v[174:175], v180 offset:0x2800
	ds_read_b64_tr_b16 v[176:177], v180 offset:0x3000
	ds_read_b64_tr_b16 v[178:179], v180 offset:0x3800
	s_waitcnt lgkmcnt(0)
	s_nop 0
	v_mfma_f32_32x32x16_bf16 v[0:15], v[146:149], v[164:167], v[0:15]
	ds_read_b64_tr_b16 v[164:165], v180 offset:0x200
	ds_read_b64_tr_b16 v[166:167], v180 offset:0xa00
	v_mfma_f32_32x32x16_bf16 v[0:15], v[150:153], v[168:171], v[0:15]
	ds_read_b64_tr_b16 v[168:169], v180 offset:0x1200
	ds_read_b64_tr_b16 v[170:171], v180 offset:0x1a00
	v_mfma_f32_32x32x16_bf16 v[0:15], v[154:157], v[172:175], v[0:15]
	ds_read_b64_tr_b16 v[172:173], v180 offset:0x2200
	ds_read_b64_tr_b16 v[174:175], v180 offset:0x2a00
	v_mfma_f32_32x32x16_bf16 v[0:15], v[158:161], v[176:179], v[0:15]
	ds_read_b64_tr_b16 v[176:177], v180 offset:0x3200
	ds_read_b64_tr_b16 v[178:179], v180 offset:0x3a00
	s_add_i32 s0, s13, 2
	s_add_i32 s1, s13, -1
	s_cmp_ge_u32 s1, s11
	s_waitcnt lgkmcnt(0)
	v_mfma_f32_32x32x16_bf16 v[16:31], v[146:149], v[164:167], v[16:31]
	ds_read_b64_tr_b16 v[164:165], v180 offset:0x400
	ds_read_b64_tr_b16 v[166:167], v180 offset:0xc00
	v_mul_f32_e32 v206, 0xbe38aa3b, v213
	v_fmamk_f32 v80, v80, 0x3e38aa3b, v206
	v_fmamk_f32 v81, v81, 0x3e38aa3b, v206
	v_mfma_f32_32x32x16_bf16 v[16:31], v[150:153], v[168:171], v[16:31]
	ds_read_b64_tr_b16 v[168:169], v180 offset:0x1400
	ds_read_b64_tr_b16 v[170:171], v180 offset:0x1c00
	v_fmamk_f32 v82, v82, 0x3e38aa3b, v206
	v_fmamk_f32 v83, v83, 0x3e38aa3b, v206
	v_mfma_f32_32x32x16_bf16 v[16:31], v[154:157], v[172:175], v[16:31]
	ds_read_b64_tr_b16 v[172:173], v180 offset:0x2400
	ds_read_b64_tr_b16 v[174:175], v180 offset:0x2c00
	v_fmamk_f32 v84, v84, 0x3e38aa3b, v206
	v_fmamk_f32 v85, v85, 0x3e38aa3b, v206
	v_mfma_f32_32x32x16_bf16 v[16:31], v[158:161], v[176:179], v[16:31]
	ds_read_b64_tr_b16 v[176:177], v180 offset:0x3400
	ds_read_b64_tr_b16 v[178:179], v180 offset:0x3c00
	v_fmamk_f32 v86, v86, 0x3e38aa3b, v206
	v_fmamk_f32 v87, v87, 0x3e38aa3b, v206
	s_waitcnt lgkmcnt(0)
	v_mfma_f32_32x32x16_bf16 v[32:47], v[146:149], v[164:167], v[32:47]
	ds_read_b64_tr_b16 v[164:165], v180 offset:0x600
	ds_read_b64_tr_b16 v[166:167], v180 offset:0xe00
	v_fmamk_f32 v88, v88, 0x3e38aa3b, v206
	v_fmamk_f32 v89, v89, 0x3e38aa3b, v206
	v_mfma_f32_32x32x16_bf16 v[32:47], v[150:153], v[168:171], v[32:47]
	ds_read_b64_tr_b16 v[168:169], v180 offset:0x1600
	ds_read_b64_tr_b16 v[170:171], v180 offset:0x1e00
	v_fmamk_f32 v90, v90, 0x3e38aa3b, v206
	v_fmamk_f32 v91, v91, 0x3e38aa3b, v206
	v_mfma_f32_32x32x16_bf16 v[32:47], v[154:157], v[172:175], v[32:47]
	ds_read_b64_tr_b16 v[172:173], v180 offset:0x2600
	ds_read_b64_tr_b16 v[174:175], v180 offset:0x2e00
	v_fmamk_f32 v92, v92, 0x3e38aa3b, v206
	v_fmamk_f32 v93, v93, 0x3e38aa3b, v206
	v_mfma_f32_32x32x16_bf16 v[32:47], v[158:161], v[176:179], v[32:47]
	ds_read_b64_tr_b16 v[176:177], v180 offset:0x3600
	ds_read_b64_tr_b16 v[178:179], v180 offset:0x3e00
	v_fmamk_f32 v94, v94, 0x3e38aa3b, v206
	v_fmamk_f32 v95, v95, 0x3e38aa3b, v206
	s_waitcnt lgkmcnt(0)
	v_mfma_f32_32x32x16_bf16 v[48:63], v[146:149], v[164:167], v[48:63]
	v_exp_f32_e32 v146, v80
	v_exp_f32_e32 v147, v81
	v_exp_f32_e32 v148, v82
	v_exp_f32_e32 v149, v83
	v_fma_f32 v164, v78, s20, v206
	v_fma_f32 v165, v79, s20, v206
	v_fma_f32 v166, v76, s20, v206
	v_fma_f32 v167, v77, s20, v206
	v_mfma_f32_32x32x16_bf16 v[48:63], v[150:153], v[168:171], v[48:63]
	v_exp_f32_e32 v150, v84
	v_exp_f32_e32 v151, v85
	v_exp_f32_e32 v152, v92
	v_exp_f32_e32 v153, v93
	v_fma_f32 v168, v74, s20, v206
	v_fma_f32 v169, v75, s20, v206
	v_fma_f32 v170, v72, s20, v206
	v_fma_f32 v171, v73, s20, v206
	v_mfma_f32_32x32x16_bf16 v[48:63], v[154:157], v[172:175], v[48:63]
	v_exp_f32_e32 v154, v94
	v_exp_f32_e32 v155, v95
	v_exp_f32_e32 v156, v90
	v_exp_f32_e32 v157, v91
	v_fma_f32 v172, v66, s20, v206
	v_fma_f32 v173, v67, s20, v206
	v_fma_f32 v174, v70, s20, v206
	v_fma_f32 v175, v71, s20, v206
	v_mfma_f32_32x32x16_bf16 v[48:63], v[158:161], v[176:179], v[48:63]
	v_exp_f32_e32 v158, v88
	v_exp_f32_e32 v159, v89
	v_exp_f32_e32 v160, v86
	v_exp_f32_e32 v161, v87
	v_fma_f32 v176, v64, s20, v206
	v_fma_f32 v177, v65, s20, v206
	v_fma_f32 v178, v68, s20, v206
	v_fma_f32 v179, v69, s20, v206
	v_add_u32_e32 v227, 0x40000, v227
	s_waitcnt vmcnt(0) lgkmcnt(0)
	s_barrier
	s_cbranch_scc1 .LBB0_256
	s_mov_b32 s13, s0
	s_mov_b32 s0, s12
	s_mov_b32 s12, s10
	s_mov_b32 s10, s4
	v_mov_b32_e32 v226, v225
	s_branch .LBB0_239

; __global__ void __launch_bounds__(NTHREADS) fwd_megakernel(Params p, int ph_lo, int ph_hi, int coop) {
;   __shared__ __attribute__((aligned(1024))) char shm[131072 + 1024];
	.amdhsa_kernel _Z14fwd_megakernel6Paramsiii
		.amdhsa_group_segment_fixed_size 132096
		.amdhsa_private_segment_fixed_size 0
		.amdhsa_kernarg_size 536
		.amdhsa_user_sgpr_count 2
		.amdhsa_user_sgpr_dispatch_ptr 0
		.amdhsa_user_sgpr_queue_ptr 0
		.amdhsa_user_sgpr_kernarg_segment_ptr 1
		.amdhsa_user_sgpr_dispatch_id 0
		.amdhsa_user_sgpr_kernarg_preload_length 0
		.amdhsa_user_sgpr_kernarg_preload_offset 0
		.amdhsa_user_sgpr_private_segment_size 0
		.amdhsa_uses_dynamic_stack 0
		.amdhsa_enable_private_segment 0
		.amdhsa_system_sgpr_workgroup_id_x 1
		.amdhsa_system_sgpr_workgroup_id_y 0
		.amdhsa_system_sgpr_workgroup_id_z 0
		.amdhsa_system_sgpr_workgroup_info 0
		.amdhsa_system_vgpr_workitem_id 2
		.amdhsa_next_free_vgpr 256
		.amdhsa_next_free_sgpr 102
		.amdhsa_accum_offset 256
		.amdhsa_reserve_vcc 1
		.amdhsa_float_round_mode_32 0
		.amdhsa_float_round_mode_16_64 0
		.amdhsa_float_denorm_mode_32 3
		.amdhsa_float_denorm_mode_16_64 3
		.amdhsa_dx10_clamp 1
		.amdhsa_ieee_mode 1
		.amdhsa_fp16_overflow 0
		.amdhsa_tg_split 0
		.amdhsa_exception_fp_ieee_invalid_op 0
		.amdhsa_exception_fp_denorm_src 0
		.amdhsa_exception_fp_ieee_div_zero 0
		.amdhsa_exception_fp_ieee_overflow 0
		.amdhsa_exception_fp_ieee_underflow 0
		.amdhsa_exception_fp_ieee_inexact 0
		.amdhsa_exception_int_div_zero 0
	.end_amdhsa_kernel

; __global__ void __launch_bounds__(NTHREADS) fwd_megakernel(Params p, int ph_lo, int ph_hi, int coop) {
;   __shared__ __attribute__((aligned(1024))) char shm[131072 + 1024];
amdhsa.kernels:
  - .agpr_count:     0
    .args:
      - .offset:         0
        .size:           264
        .value_kind:     by_value
      - .offset:         264
        .size:           4
        .value_kind:     by_value
      - .offset:         268
        .size:           4
        .value_kind:     by_value
      - .offset:         272
        .size:           4
        .value_kind:     by_value
      - .offset:         280
        .size:           4
        .value_kind:     hidden_block_count_x
      - .offset:         284
        .size:           4
        .value_kind:     hidden_block_count_y
      - .offset:         288
        .size:           4
        .value_kind:     hidden_block_count_z
      - .offset:         292
        .size:           2
        .value_kind:     hidden_group_size_x
      - .offset:         294
        .size:           2
        .value_kind:     hidden_group_size_y
      - .offset:         296
        .size:           2
        .value_kind:     hidden_group_size_z
      - .offset:         298
        .size:           2
        .value_kind:     hidden_remainder_x
      - .offset:         300
        .size:           2
        .value_kind:     hidden_remainder_y
      - .offset:         302
        .size:           2
        .value_kind:     hidden_remainder_z
      - .offset:         320
        .size:           8
        .value_kind:     hidden_global_offset_x
      - .offset:         328
        .size:           8
        .value_kind:     hidden_global_offset_y
      - .offset:         336
        .size:           8
        .value_kind:     hidden_global_offset_z
      - .offset:         344
        .size:           2
        .value_kind:     hidden_grid_dims
      - .offset:         368
        .size:           8
        .value_kind:     hidden_multigrid_sync_arg
    .group_segment_fixed_size: 132096
    .kernarg_segment_align: 8
    .kernarg_segment_size: 536
    .language:       OpenCL C
    .language_version:
      - 2
      - 0
    .max_flat_workgroup_size: 512
    .name:           _Z14fwd_megakernel6Paramsiii
    .private_segment_fixed_size: 0
    .sgpr_count:     108
    .sgpr_spill_count: 170
    .symbol:         _Z14fwd_megakernel6Paramsiii.kd
    .uniform_work_group_size: 1
    .uses_dynamic_stack: false
    .vgpr_count:     256
    .vgpr_spill_count: 0
    .wavefront_size: 64
